# static s_setprio 1 for waves 4-7 during the five GEMM phases (reset to 0 before each barrier), on top of v14b
# baseline (speedup 1.0000x reference)
;     constexpr int RM = 64 * TB;
;     const int lane = tid & 63, w = tid >> 6, wt = w >> 2, wf = w & 3, r = lane & 31, hh = lane >> 5;
;     const int wu = __builtin_amdgcn_readfirstlane(w);
.LBB0_189:
	v_readfirstlane_b32 s32, v202
	s_cmp_lt_u32 s32, 0x100
	s_cbranch_scc1 .Lprio2_skip
	s_setprio 1

; DI unsigned xb_ld(unsigned* p)              { return __hip_atomic_load(p, __ATOMIC_RELAXED, __HIP_MEMORY_SCOPE_AGENT); }
; DI void xcd_barrier_complete(unsigned* bar, unsigned x, unsigned& nloc, unsigned& nx) {
;     const unsigned G = gridDim.x * gridDim.y * gridDim.z;
;     unsigned sum, cnt, mine, sp = 0u;
;     for (;;) {
;         sum = 0u; cnt = 0u; mine = 0u;
; #pragma unroll
;         for (unsigned j = 0; j < 16; ++j) { const unsigned c = xb_ld(&bar[XB_XCNT(j)]); sum += c; cnt += (c > 0u) ? 1u : 0u; mine = (j == x) ? c : mine; }
; DI void xcd_barrier(const XcdBarrier& b) {
;     asm volatile("s_waitcnt vmcnt(0)" ::: "memory");
;     __syncthreads();
;     if (threadIdx.x == 0) {
;         unsigned* bar = b.bar;
;         __builtin_amdgcn_s_waitcnt(0);
;         unsigned nloc = b.st[0], nx = b.st[1];
;         if (nloc == 0u) { xcd_barrier_complete(bar, b.x, nloc, nx); b.st[0] = nloc; b.st[1] = nx; }
.LBB0_317:
	s_setprio 0
	s_cmp_gt_i32 s25, 3
	s_cselect_b64 s[4:5], -1, 0
	s_and_b64 s[0:1], s[8:9], s[4:5]
	s_andn2_b64 vcc, exec, s[0:1]
	s_cbranch_vccnz .LBB0_367
	s_waitcnt vmcnt(0)
	s_waitcnt vmcnt(0) lgkmcnt(0)
	s_barrier
	s_and_saveexec_b64 s[6:7], s[70:71]
	s_cbranch_execz .LBB0_366
	v_mov_b32_e32 v0, 0
	s_waitcnt vmcnt(0) expcnt(0) lgkmcnt(0)
	ds_read_b32 v2, v0
	ds_read_b32 v1, v0 offset:4
	s_waitcnt lgkmcnt(1)
	v_cmp_ne_u32_e32 vcc, 0, v2
	s_cbranch_vccnz .LBB0_334
	s_add_u32 s8, s30, 0xf0b8200
	s_addc_u32 s9, s31, 0
	s_add_u32 s10, s30, 0xf0b8400
	s_addc_u32 s11, s31, 0
	s_add_u32 s12, s30, 0xf0b8500
	s_addc_u32 s13, s31, 0
	s_add_u32 s14, s30, 0xf0b8600
	s_addc_u32 s15, s31, 0
	s_add_u32 s16, s30, 0xf0b8700
	s_addc_u32 s17, s31, 0
	s_add_u32 s18, s30, 0xf0b8800
	s_addc_u32 s19, s31, 0
	s_add_u32 s38, s30, 0xf0b8900
	s_addc_u32 s39, s31, 0
	s_add_u32 s42, s30, 0xf0b8a00
	s_addc_u32 s43, s31, 0
	s_add_u32 s44, s30, 0xf0b8b00
	s_addc_u32 s45, s31, 0
	s_add_u32 s54, s30, 0xf0b8c00
	s_addc_u32 s55, s31, 0
	s_add_u32 s58, s30, 0xf0b8d00
	s_addc_u32 s59, s31, 0
	s_add_u32 s60, s30, 0xf0b8e00
	s_addc_u32 s61, s31, 0
	s_add_u32 s62, s30, 0xf0b8f00
	s_addc_u32 s63, s31, 0
	s_add_u32 s64, s30, 0xf0b9000
	s_addc_u32 s65, s31, 0
	s_load_dwordx2 s[0:1], s[72:73], 0xb8
	s_load_dword s3, s[72:73], 0xc0
	s_add_u32 s66, s30, 0xf0b9100
	s_addc_u32 s67, s31, 0
	s_add_u32 s70, s30, 0xf0b9200
	s_addc_u32 s71, s31, 0
	s_waitcnt lgkmcnt(0)
	s_mul_i32 s0, s1, s0
	s_add_u32 s72, s30, 0xf0b9300
	s_mul_i32 s0, s0, s3
	s_addc_u32 s73, s31, 0
	s_mov_b32 s1, 1
	s_branch .LBB0_322

; DI unsigned xb_ld(unsigned* p)              { return __hip_atomic_load(p, __ATOMIC_RELAXED, __HIP_MEMORY_SCOPE_AGENT); }
; DI void xcd_barrier_complete(unsigned* bar, unsigned x, unsigned& nloc, unsigned& nx) {
;     const unsigned G = gridDim.x * gridDim.y * gridDim.z;
;     unsigned sum, cnt, mine, sp = 0u;
;     for (;;) {
;         sum = 0u; cnt = 0u; mine = 0u;
; #pragma unroll
;         for (unsigned j = 0; j < 16; ++j) { const unsigned c = xb_ld(&bar[XB_XCNT(j)]); sum += c; cnt += (c > 0u) ? 1u : 0u; mine = (j == x) ? c : mine; }
; DI void xcd_barrier(const XcdBarrier& b) {
;     asm volatile("s_waitcnt vmcnt(0)" ::: "memory");
;     __syncthreads();
;     if (threadIdx.x == 0) {
;         unsigned* bar = b.bar;
;         __builtin_amdgcn_s_waitcnt(0);
;         unsigned nloc = b.st[0], nx = b.st[1];
;         if (nloc == 0u) { xcd_barrier_complete(bar, b.x, nloc, nx); b.st[0] = nloc; b.st[1] = nx; }
.LBB0_577:
	s_setprio 0
	s_cmp_gt_i32 s25, 5
	s_cselect_b64 s[4:5], -1, 0
	s_and_b64 s[0:1], s[8:9], s[4:5]
	s_andn2_b64 vcc, exec, s[0:1]
	s_cbranch_vccnz .LBB0_627
	s_waitcnt vmcnt(0)
	s_waitcnt vmcnt(0) lgkmcnt(0)
	s_barrier
	s_and_saveexec_b64 s[6:7], s[70:71]
	s_cbranch_execz .LBB0_626
	v_mov_b32_e32 v0, 0
	s_waitcnt vmcnt(0) expcnt(0) lgkmcnt(0)
	ds_read_b32 v2, v0
	ds_read_b32 v1, v0 offset:4
	s_waitcnt lgkmcnt(1)
	v_cmp_ne_u32_e32 vcc, 0, v2
	s_cbranch_vccnz .LBB0_594
	s_add_u32 s8, s30, 0xf0b8200
	s_addc_u32 s9, s31, 0
	s_add_u32 s10, s30, 0xf0b8400
	s_addc_u32 s11, s31, 0
	s_add_u32 s12, s30, 0xf0b8500
	s_addc_u32 s13, s31, 0
	s_add_u32 s14, s30, 0xf0b8600
	s_addc_u32 s15, s31, 0
	s_add_u32 s16, s30, 0xf0b8700
	s_addc_u32 s17, s31, 0
	s_add_u32 s18, s30, 0xf0b8800
	s_addc_u32 s19, s31, 0
	s_add_u32 s20, s30, 0xf0b8900
	s_addc_u32 s21, s31, 0
	s_add_u32 s22, s30, 0xf0b8a00
	s_addc_u32 s23, s31, 0
	s_add_u32 s24, s30, 0xf0b8b00
	s_addc_u32 s25, s31, 0
	s_add_u32 s36, s30, 0xf0b8c00
	s_addc_u32 s37, s31, 0
	s_add_u32 s38, s30, 0xf0b8d00
	s_addc_u32 s39, s31, 0
	s_add_u32 s42, s30, 0xf0b8e00
	s_addc_u32 s43, s31, 0
	s_add_u32 s44, s30, 0xf0b8f00
	s_addc_u32 s45, s31, 0
	s_add_u32 s46, s30, 0xf0b9000
	s_addc_u32 s47, s31, 0
	s_load_dwordx2 s[0:1], s[72:73], 0xb8
	s_load_dword s3, s[72:73], 0xc0
	s_add_u32 s48, s30, 0xf0b9100
	s_addc_u32 s49, s31, 0
	s_add_u32 s50, s30, 0xf0b9200
	s_addc_u32 s51, s31, 0
	s_waitcnt lgkmcnt(0)
	s_mul_i32 s0, s1, s0
	s_add_u32 s52, s30, 0xf0b9300
	s_mul_i32 s0, s0, s3
	s_addc_u32 s53, s31, 0
	s_mov_b32 s1, 1
	s_branch .LBB0_582

; DI unsigned xb_ld(unsigned* p)              { return __hip_atomic_load(p, __ATOMIC_RELAXED, __HIP_MEMORY_SCOPE_AGENT); }
; DI void xcd_barrier_complete(unsigned* bar, unsigned x, unsigned& nloc, unsigned& nx) {
;     const unsigned G = gridDim.x * gridDim.y * gridDim.z;
;     unsigned sum, cnt, mine, sp = 0u;
;     for (;;) {
;         sum = 0u; cnt = 0u; mine = 0u;
; #pragma unroll
;         for (unsigned j = 0; j < 16; ++j) { const unsigned c = xb_ld(&bar[XB_XCNT(j)]); sum += c; cnt += (c > 0u) ? 1u : 0u; mine = (j == x) ? c : mine; }
; DI void xcd_barrier(const XcdBarrier& b) {
;     asm volatile("s_waitcnt vmcnt(0)" ::: "memory");
;     __syncthreads();
;     if (threadIdx.x == 0) {
;         unsigned* bar = b.bar;
;         __builtin_amdgcn_s_waitcnt(0);
;         unsigned nloc = b.st[0], nx = b.st[1];
;         if (nloc == 0u) { xcd_barrier_complete(bar, b.x, nloc, nx); b.st[0] = nloc; b.st[1] = nx; }
.LBB0_921:
	s_setprio 0
	s_cmp_gt_i32 s25, 7
	s_cselect_b64 s[0:1], -1, 0
	s_and_b64 s[0:1], s[14:15], s[0:1]
	s_andn2_b64 vcc, exec, s[0:1]
	s_cbranch_vccnz .LBB0_971
	s_waitcnt vmcnt(0)
	s_waitcnt vmcnt(0) lgkmcnt(0)
	s_barrier
	s_and_saveexec_b64 s[4:5], s[70:71]
	s_cbranch_execz .LBB0_970
	v_mov_b32_e32 v0, 0
	s_waitcnt vmcnt(0) expcnt(0) lgkmcnt(0)
	ds_read_b32 v2, v0
	ds_read_b32 v1, v0 offset:4
	s_waitcnt lgkmcnt(1)
	v_cmp_ne_u32_e32 vcc, 0, v2
	s_cbranch_vccnz .LBB0_938
	s_add_u32 s6, s30, 0xf0b8200
	s_addc_u32 s7, s31, 0
	s_add_u32 s8, s30, 0xf0b8400
	s_addc_u32 s9, s31, 0
	s_add_u32 s10, s30, 0xf0b8500
	s_addc_u32 s11, s31, 0
	s_add_u32 s12, s30, 0xf0b8600
	s_addc_u32 s13, s31, 0
	s_add_u32 s14, s30, 0xf0b8700
	s_addc_u32 s15, s31, 0
	s_add_u32 s16, s30, 0xf0b8800
	s_addc_u32 s17, s31, 0
	s_add_u32 s18, s30, 0xf0b8900
	s_addc_u32 s19, s31, 0
	s_add_u32 s20, s30, 0xf0b8a00
	s_addc_u32 s21, s31, 0
	s_add_u32 s22, s30, 0xf0b8b00
	s_addc_u32 s23, s31, 0
	s_add_u32 s24, s30, 0xf0b8c00
	s_addc_u32 s25, s31, 0
	s_add_u32 s36, s30, 0xf0b8d00
	s_addc_u32 s37, s31, 0
	s_add_u32 s38, s30, 0xf0b8e00
	s_addc_u32 s39, s31, 0
	s_add_u32 s40, s30, 0xf0b8f00
	s_addc_u32 s41, s31, 0
	s_add_u32 s42, s30, 0xf0b9000
	s_addc_u32 s43, s31, 0
	s_load_dwordx2 s[0:1], s[72:73], 0xb8
	s_load_dword s3, s[72:73], 0xc0
	s_add_u32 s44, s30, 0xf0b9100
	s_addc_u32 s45, s31, 0
	s_add_u32 s46, s30, 0xf0b9200
	s_addc_u32 s47, s31, 0
	s_waitcnt lgkmcnt(0)
	s_mul_i32 s0, s1, s0
	s_add_u32 s48, s30, 0xf0b9300
	s_mul_i32 s0, s0, s3
	s_addc_u32 s49, s31, 0
	s_mov_b32 s1, 1
	s_branch .LBB0_926

; DI unsigned xb_ld(unsigned* p)              { return __hip_atomic_load(p, __ATOMIC_RELAXED, __HIP_MEMORY_SCOPE_AGENT); }
; DI void xcd_barrier_complete(unsigned* bar, unsigned x, unsigned& nloc, unsigned& nx) {
;     const unsigned G = gridDim.x * gridDim.y * gridDim.z;
;     unsigned sum, cnt, mine, sp = 0u;
;     for (;;) {
;         sum = 0u; cnt = 0u; mine = 0u;
; #pragma unroll
;         for (unsigned j = 0; j < 16; ++j) { const unsigned c = xb_ld(&bar[XB_XCNT(j)]); sum += c; cnt += (c > 0u) ? 1u : 0u; mine = (j == x) ? c : mine; }
; DI void xcd_barrier(const XcdBarrier& b) {
;     asm volatile("s_waitcnt vmcnt(0)" ::: "memory");
;     __syncthreads();
;     if (threadIdx.x == 0) {
;         unsigned* bar = b.bar;
;         __builtin_amdgcn_s_waitcnt(0);
;         unsigned nloc = b.st[0], nx = b.st[1];
;         if (nloc == 0u) { xcd_barrier_complete(bar, b.x, nloc, nx); b.st[0] = nloc; b.st[1] = nx; }
.LBB0_1012:
	s_setprio 0
	s_cmp_gt_i32 s25, 9
	s_cselect_b64 s[4:5], -1, 0
	s_and_b64 s[0:1], s[8:9], s[4:5]
	s_andn2_b64 vcc, exec, s[0:1]
	s_cbranch_vccnz .LBB0_1062
	s_waitcnt vmcnt(0)
	s_waitcnt vmcnt(0) lgkmcnt(0)
	s_barrier
	s_and_saveexec_b64 s[6:7], s[70:71]
	s_cbranch_execz .LBB0_1061
	v_mov_b32_e32 v0, 0
	s_waitcnt vmcnt(0) expcnt(0) lgkmcnt(0)
	ds_read_b32 v2, v0
	ds_read_b32 v1, v0 offset:4
	s_waitcnt lgkmcnt(1)
	v_cmp_ne_u32_e32 vcc, 0, v2
	s_cbranch_vccnz .LBB0_1029
	s_add_u32 s8, s30, 0xf0b8200
	s_addc_u32 s9, s31, 0
	s_add_u32 s10, s30, 0xf0b8400
	s_addc_u32 s11, s31, 0
	s_add_u32 s12, s30, 0xf0b8500
	s_addc_u32 s13, s31, 0
	s_add_u32 s14, s30, 0xf0b8600
	s_addc_u32 s15, s31, 0
	s_add_u32 s16, s30, 0xf0b8700
	s_addc_u32 s17, s31, 0
	s_add_u32 s18, s30, 0xf0b8800
	s_addc_u32 s19, s31, 0
	s_add_u32 s20, s30, 0xf0b8900
	s_addc_u32 s21, s31, 0
	s_add_u32 s22, s30, 0xf0b8a00
	s_addc_u32 s23, s31, 0
	s_add_u32 s24, s30, 0xf0b8b00
	s_addc_u32 s25, s31, 0
	s_add_u32 s36, s30, 0xf0b8c00
	s_addc_u32 s37, s31, 0
	s_add_u32 s38, s30, 0xf0b8d00
	s_addc_u32 s39, s31, 0
	s_add_u32 s40, s30, 0xf0b8e00
	s_addc_u32 s41, s31, 0
	s_add_u32 s42, s30, 0xf0b8f00
	s_addc_u32 s43, s31, 0
	s_add_u32 s44, s30, 0xf0b9000
	s_addc_u32 s45, s31, 0
	s_load_dwordx2 s[0:1], s[72:73], 0xb8
	s_load_dword s3, s[72:73], 0xc0
	s_add_u32 s46, s30, 0xf0b9100
	s_addc_u32 s47, s31, 0
	s_add_u32 s48, s30, 0xf0b9200
	s_addc_u32 s49, s31, 0
	s_waitcnt lgkmcnt(0)
	s_mul_i32 s0, s1, s0
	s_add_u32 s50, s30, 0xf0b9300
	s_mul_i32 s0, s0, s3
	s_addc_u32 s51, s31, 0
	s_mov_b32 s1, 1
	s_branch .LBB0_1017

; DI unsigned xb_ld(unsigned* p)              { return __hip_atomic_load(p, __ATOMIC_RELAXED, __HIP_MEMORY_SCOPE_AGENT); }
; DI void xcd_barrier_complete(unsigned* bar, unsigned x, unsigned& nloc, unsigned& nx) {
;     const unsigned G = gridDim.x * gridDim.y * gridDim.z;
;     unsigned sum, cnt, mine, sp = 0u;
;     for (;;) {
;         sum = 0u; cnt = 0u; mine = 0u;
; #pragma unroll
;         for (unsigned j = 0; j < 16; ++j) { const unsigned c = xb_ld(&bar[XB_XCNT(j)]); sum += c; cnt += (c > 0u) ? 1u : 0u; mine = (j == x) ? c : mine; }
; DI void xcd_barrier(const XcdBarrier& b) {
;     asm volatile("s_waitcnt vmcnt(0)" ::: "memory");
;     __syncthreads();
;     if (threadIdx.x == 0) {
;         unsigned* bar = b.bar;
;         __builtin_amdgcn_s_waitcnt(0);
;         unsigned nloc = b.st[0], nx = b.st[1];
;         if (nloc == 0u) { xcd_barrier_complete(bar, b.x, nloc, nx); b.st[0] = nloc; b.st[1] = nx; }
.LBB0_1179:
	s_setprio 0
	s_cmp_gt_i32 s25, 11
	s_cselect_b64 s[4:5], -1, 0
	s_and_b64 s[0:1], s[6:7], s[4:5]
	s_andn2_b64 vcc, exec, s[0:1]
	s_cbranch_vccnz .LBB0_1229
	s_waitcnt vmcnt(0)
	s_waitcnt vmcnt(0) lgkmcnt(0)
	s_barrier
	s_and_saveexec_b64 s[6:7], s[70:71]
	s_cbranch_execz .LBB0_1228
	v_mov_b32_e32 v0, 0
	s_waitcnt vmcnt(0) expcnt(0) lgkmcnt(0)
	ds_read_b32 v2, v0
	ds_read_b32 v1, v0 offset:4
	s_waitcnt lgkmcnt(1)
	v_cmp_ne_u32_e32 vcc, 0, v2
	s_cbranch_vccnz .LBB0_1196
	s_add_u32 s8, s30, 0xf0b8200
	s_addc_u32 s9, s31, 0
	s_add_u32 s10, s30, 0xf0b8400
	s_addc_u32 s11, s31, 0
	s_add_u32 s12, s30, 0xf0b8500
	s_addc_u32 s13, s31, 0
	s_add_u32 s14, s30, 0xf0b8600
	s_addc_u32 s15, s31, 0
	s_add_u32 s16, s30, 0xf0b8700
	s_addc_u32 s17, s31, 0
	s_add_u32 s18, s30, 0xf0b8800
	s_addc_u32 s19, s31, 0
	s_add_u32 s20, s30, 0xf0b8900
	s_addc_u32 s21, s31, 0
	s_add_u32 s22, s30, 0xf0b8a00
	s_addc_u32 s23, s31, 0
	s_add_u32 s24, s30, 0xf0b8b00
	s_addc_u32 s25, s31, 0
	s_add_u32 s36, s30, 0xf0b8c00
	s_addc_u32 s37, s31, 0
	s_add_u32 s38, s30, 0xf0b8d00
	s_addc_u32 s39, s31, 0
	s_add_u32 s40, s30, 0xf0b8e00
	s_addc_u32 s41, s31, 0
	s_add_u32 s42, s30, 0xf0b8f00
	s_addc_u32 s43, s31, 0
	s_add_u32 s44, s30, 0xf0b9000
	s_addc_u32 s45, s31, 0
	s_load_dwordx2 s[0:1], s[72:73], 0xb8
	s_load_dword s3, s[72:73], 0xc0
	s_add_u32 s46, s30, 0xf0b9100
	s_addc_u32 s47, s31, 0
	s_add_u32 s48, s30, 0xf0b9200
	s_addc_u32 s49, s31, 0
	s_waitcnt lgkmcnt(0)
	s_mul_i32 s0, s1, s0
	s_add_u32 s50, s30, 0xf0b9300
	s_mul_i32 s0, s0, s3
	s_addc_u32 s51, s31, 0
	s_mov_b32 s1, 1
	s_branch .LBB0_1184
